# guarded XCD-aware mapping with nop pads so that the six hot loops sit at the same byte phase (mod 64) as in the unguarded version
# speedup vs baseline: 1.0004x; 1.0004x over previous
; template <int MB, bool PF2 = true>
; DI void gemm_main(const u16* __restrict__ A, int lda, const u16* __restrict__ B, int ldb, int K, f32x16 (&acc)[MB][2], GemmLds* s, int tid) {
;   const int lane = tid & 63, w = tid >> 6, r = lane & 31, h = lane >> 5, wm = w >> 1, wn = w & 1;
;   const int srow = tid >> 3, skc = (tid & 7) * 8;
;   const unsigned oa0 = (unsigned)(srow * lda + skc) * 2u, oa1 = oa0 + 64u * lda, oa2 = oa0 + 128u * lda, oa3 = oa0 + 192u * lda;
;   const unsigned ob0 = (unsigned)(srow * ldb + skc) * 2u, ob1 = ob0 + 64u * ldb, ob2 = ob0 + 128u * ldb, ob3 = ob0 + 192u * ldb;
; DI void phase_inproj(const Params& p, int l, char* smem, int tid) {
;   const int lane = tid & 63, w = tid >> 6, r = lane & 31, h = lane >> 5, wm = w >> 1, wn = w & 1;
;   GemmLds* s = (GemmLds*)smem;
;   const u16* Wt = p.WtIn + (size_t)l * 3072 * 1024;
;   for (int it = blockIdx.x; it < 272 * 24; it += gridDim.x) {
;     const int mt = it / 24, nt = it % 24, m0 = mt * 128, n0 = nt * 128;
;     f32x16 acc[2][2]; zero_acc<2>(acc);
;     gemm_main<2>(p.xn + (size_t)m0 * 1024, 1024, Wt + (size_t)n0 * 1024, 1024, 1024, acc, s, tid);
.LBB0_515:
	v_readlane_b32 s0, v253, 14
	v_readlane_b32 s1, v253, 15
	v_mov_b32_e32 v0, v206
	s_andn2_b64 vcc, exec, s[0:1]
	s_cbranch_vccnz .LBB0_550
	s_nop 0
	s_nop 0
	s_nop 0
	s_nop 0
	s_nop 0
	s_nop 0
	s_nop 0
	s_nop 0
	s_nop 0
	v_readlane_b32 s0, v254, 19
	v_and_b32_e32 v113, 63, v206
	v_lshrrev_b32_e32 v114, 6, v206
	v_lshrrev_b32_e32 v115, 3, v113
	v_lshl_add_u32 v115, v114, 5, v115
	v_lshlrev_b32_e32 v115, 11, v115
	v_and_b32_e32 v116, 7, v113
	v_lshrrev_b32_e32 v113, 4, v113
	v_xor_b32_e32 v116, v116, v113
	v_lshl_or_b32 v98, v116, 4, v115
	v_xor_b32_e32 v99, 64, v98
	v_add_u32_e32 v99, 16384, v99
	v_add_u32_e32 v100, 32768, v98
	v_add_u32_e32 v101, 32768, v99
	v_lshrrev_b32_e32 v117, 6, v206
	v_and_b32_e32 v113, 31, v206
	v_bfe_u32 v114, v206, 5, 1
	v_bfe_u32 v115, v113, 1, 3
	v_xor_b32_e32 v115, v115, v114
	v_lshlrev_b32_e32 v115, 4, v115
	v_lshl_or_b32 v115, v113, 7, v115
	v_lshrrev_b32_e32 v116, 7, v206
	v_lshl_add_u32 v102, v116, 13, v115
	v_bfe_u32 v116, v206, 6, 1
	v_lshl_add_u32 v106, v116, 13, v115
	v_add_u32_e32 v106, 0x4000, v106
	v_xor_b32_e32 v103, 32, v102
	v_xor_b32_e32 v107, 32, v106
	v_xor_b32_e32 v104, 64, v102
	v_xor_b32_e32 v108, 64, v106
	v_xor_b32_e32 v105, 96, v102
	v_xor_b32_e32 v109, 96, v106
	v_and_b32_e32 v113, 31, v206
	v_lshrrev_b32_e32 v114, 7, v206
	v_lshl_add_u32 v113, v114, 6, v113
	v_bfe_u32 v115, v206, 5, 1
	v_lshlrev_b32_e32 v116, 3, v115
	v_mul_u32_u24_e32 v110, 0xe00, v113
	v_add_u32_e32 v110, v110, v116
	v_mul_u32_u24_e32 v111, 0x640, v113
	v_add_u32_e32 v111, v111, v116
	v_mul_u32_u24_e32 v116, 0x8800, v115
	v_lshl_add_u32 v112, v113, 1, v116
	v_lshrrev_b32_e32 v113, 6, v206
	v_mul_u32_u24_e32 v113, 0x2400, v113
	v_add_u32_e32 v113, 0x8000, v113
	v_and_b32_e32 v114, 31, v206
	v_mul_u32_u24_e32 v114, 0x90, v114
	v_bfe_u32 v115, v206, 5, 1
	v_lshl_add_u32 v114, v115, 3, v114
	v_add_u32_e32 v118, v113, v114
	v_bfe_u32 v114, v206, 3, 3
	v_mul_u32_u24_e32 v114, 0x90, v114
	v_and_b32_e32 v115, 7, v206
	v_lshl_add_u32 v114, v115, 4, v114
	v_add_u32_e32 v119, v113, v114
	v_bfe_u32 v113, v206, 3, 3
	v_lshrrev_b32_e32 v114, 7, v206
	v_lshl_add_u32 v113, v114, 6, v113
	v_mul_u32_u24_e32 v113, 0xe00, v113
	v_bfe_u32 v114, v206, 6, 1
	v_lshlrev_b32_e32 v114, 7, v114
	v_and_b32_e32 v115, 7, v206
	v_lshl_or_b32 v114, v115, 4, v114
	v_add_u32_e32 v120, v113, v114
	v_bfe_u32 v113, v206, 3, 3
	v_lshrrev_b32_e32 v114, 7, v206
	v_lshl_add_u32 v113, v114, 6, v113
	v_mul_u32_u24_e32 v113, 0x640, v113
	v_bfe_u32 v114, v206, 6, 1
	v_lshlrev_b32_e32 v114, 7, v114
	v_and_b32_e32 v115, 7, v206
	v_lshl_or_b32 v114, v115, 4, v114
	v_add_u32_e32 v121, v113, v114
	v_readfirstlane_b32 s10, v117
	s_lshl_b32 s10, s10, 12
	s_mul_i32 s1, s0, 0x600000
	s_add_u32 s14, s96, 0x1ab20000
	s_addc_u32 s15, s97, 0
	s_add_u32 s14, s14, s1
	s_addc_u32 s15, s15, 0
	v_readlane_b32 s0, v254, 19
	s_getreg_b32 s16, hwreg(HW_REG_XCC_ID, 0, 4)
	v_mov_b32_e32 v116, 0x125f0
	ds_read_b32 v114, v116 offset:16
	ds_read_b32 v113, v116 offset:20
	s_waitcnt lgkmcnt(0)
	v_readfirstlane_b32 s2, v113
	s_mov_b32 s12, s48
	s_mov_b32 s17, s49
	s_cmp_eq_u32 s2, 8
	s_cbranch_scc0 .Lipx_flat
	s_cmp_eq_u32 s10, 0
	s_cbranch_scc0 .Lipx_wait
	s_mov_b64 s[6:7], exec
	s_mov_b64 exec, 1
	s_lshl_b32 s8, s16, 8
	s_lshl_b32 s9, s0, 11
	s_add_u32 s8, s8, s9
	s_add_u32 s8, s8, 0x1da60000
	s_add_u32 s8, s96, s8
	s_addc_u32 s9, s97, 0
	v_mov_b32_e32 v113, 1
	v_mov_b32_e32 v115, 0
	global_atomic_add v115, v115, v113, s[8:9] sc0
	s_waitcnt vmcnt(0)
	ds_write_b32 v116, v115
	s_waitcnt lgkmcnt(0)
	s_mov_b64 exec, s[6:7]

; DI int launder_i(int v) { asm volatile("" : "+v"(v)); return v; }
; #define GRID_BAR() xcd_barrier((unsigned*)(ka.ws + OFF_BAR), xb_xcc_id(), (volatile unsigned*)&xb_words)
; __global__ void __launch_bounds__(256, 2) mega_kernel(KArgs ka) {
;     ...
;     { Params p = make_params(ka); phase_inproj(p, l, smem, launder_i(tid)); } GRID_BAR();
.Lip_done:
	s_nop 0
	s_nop 0
	s_waitcnt vmcnt(0) lgkmcnt(0)

; template <int MB, bool PF2 = true>
; DI void gemm_main(const u16* __restrict__ A, int lda, const u16* __restrict__ B, int ldb, int K, f32x16 (&acc)[MB][2], GemmLds* s, int tid) {
;   const int lane = tid & 63, w = tid >> 6, r = lane & 31, h = lane >> 5, wm = w >> 1, wn = w & 1;
;   const int srow = tid >> 3, skc = (tid & 7) * 8;
;   const unsigned oa0 = (unsigned)(srow * lda + skc) * 2u, oa1 = oa0 + 64u * lda, oa2 = oa0 + 128u * lda, oa3 = oa0 + 192u * lda;
;   const unsigned ob0 = (unsigned)(srow * ldb + skc) * 2u, ob1 = ob0 + 64u * ldb, ob2 = ob0 + 128u * ldb, ob3 = ob0 + 192u * ldb;
; DI void phase_merge(const Params& p, int l, char* smem, int tid) {
;   const int lane = tid & 63, w = tid >> 6, r = lane & 31, h = lane >> 5, wm = w >> 1, wn = w & 1;
;   GemmLds* s = (GemmLds*)smem;
;   u16* ACC = p.Pk;
;   const bool dyn = (l == 0);
;   unsigned* qc = p.bar + 4096 + 320;
;   for (int it = (dyn ? fetch_item(qc, smem) : (int)blockIdx.x); it < 544 * 8; it = (dyn ? fetch_item(qc, smem) : it + (int)gridDim.x)) {
.LBB0_1140:
	s_or_b64 exec, exec, s[0:1]
	v_readlane_b32 s2, v254, 17
	v_readlane_b32 s3, v254, 18
	v_mov_b32_e32 v0, v206
	s_andn2_b64 vcc, exec, s[2:3]
	v_cndmask_b32_e64 v2, 0, 1, s[2:3]
	v_cmp_ne_u32_e64 s[0:1], 1, v2
	v_mov_b32_e32 v149, s48
	s_waitcnt lgkmcnt(0)
	s_barrier
	v_readlane_b32 s18, v254, 19
	v_and_b32_e32 v147, 63, v206
	v_lshrrev_b32_e32 v149, 6, v206
	v_lshrrev_b32_e32 v151, 3, v147
	v_lshl_add_u32 v151, v149, 5, v151
	v_lshlrev_b32_e32 v151, 11, v151
	v_and_b32_e32 v153, 7, v147
	v_lshrrev_b32_e32 v147, 4, v147
	v_xor_b32_e32 v153, v153, v147
	v_lshl_or_b32 v200, v153, 4, v151
	v_xor_b32_e32 v201, 64, v200
	v_add_u32_e32 v201, 16384, v201
	v_add_u32_e32 v202, 32768, v200
	v_add_u32_e32 v203, 32768, v201
	v_and_b32_e32 v147, 63, v206
	v_lshrrev_b32_e32 v149, 6, v206
	v_lshrrev_b32_e32 v151, 3, v147
	v_lshl_add_u32 v151, v149, 5, v151
	v_lshlrev_b32_e32 v151, 9, v151
	v_and_b32_e32 v153, 7, v147
	v_lshrrev_b32_e32 v147, 4, v147
	v_xor_b32_e32 v153, v153, v147
	v_lshl_or_b32 v130, v153, 4, v151
	v_xor_b32_e32 v131, 64, v130
	v_add_u32_e32 v131, 4096, v131
	v_add_u32_e32 v132, 8192, v130
	v_add_u32_e32 v133, 8192, v131
	v_lshrrev_b32_e32 v204, 6, v206
	v_and_b32_e32 v147, 31, v206
	v_bfe_u32 v149, v206, 5, 1
	v_bfe_u32 v151, v147, 1, 3
	v_xor_b32_e32 v151, v151, v149
	v_lshlrev_b32_e32 v151, 4, v151
	v_lshl_or_b32 v151, v147, 7, v151
	v_lshrrev_b32_e32 v153, 7, v206
	v_lshl_add_u32 v138, v153, 13, v151
	v_bfe_u32 v153, v206, 6, 1
	v_lshl_add_u32 v142, v153, 13, v151
	v_add_u32_e32 v142, 0x4000, v142
	v_xor_b32_e32 v139, 32, v138
	v_xor_b32_e32 v143, 32, v142
	v_xor_b32_e32 v140, 64, v138
	v_xor_b32_e32 v144, 64, v142
	v_xor_b32_e32 v141, 96, v138
	v_xor_b32_e32 v145, 96, v142
	v_and_b32_e32 v147, 31, v206
	v_lshrrev_b32_e32 v149, 7, v206
	v_lshl_add_u32 v147, v149, 6, v147
	v_lshlrev_b32_e32 v147, 11, v147
	v_bfe_u32 v149, v206, 6, 1
	v_lshlrev_b32_e32 v149, 7, v149
	v_bfe_u32 v151, v206, 5, 1
	v_lshl_or_b32 v149, v151, 3, v149
	v_or_b32_e32 v146, v147, v149
	v_lshrrev_b32_e32 v147, 6, v206
	v_mul_u32_u24_e32 v147, 0x2400, v147
	v_and_b32_e32 v149, 31, v206
	v_mul_u32_u24_e32 v149, 0x90, v149
	v_bfe_u32 v151, v206, 5, 1
	v_lshl_add_u32 v149, v151, 3, v149
	v_add_u32_e32 v134, v147, v149
	v_bfe_u32 v149, v206, 3, 3
	v_mul_u32_u24_e32 v149, 0x90, v149
	v_and_b32_e32 v151, 7, v206
	v_lshl_add_u32 v149, v151, 4, v149
	v_add_u32_e32 v135, v147, v149
	v_bfe_u32 v147, v206, 3, 3
	v_lshrrev_b32_e32 v149, 7, v206
	v_lshl_add_u32 v147, v149, 6, v147
	v_mul_u32_u24_e32 v147, 0x800, v147
	v_bfe_u32 v149, v206, 6, 1
	v_lshlrev_b32_e32 v149, 7, v149
	v_and_b32_e32 v151, 7, v206
	v_lshl_or_b32 v149, v151, 4, v149
	v_add_u32_e32 v136, v147, v149
	v_readfirstlane_b32 s10, v204
	s_lshl_b32 s10, s10, 12
	s_lshl_b32 s6, s18, 23
	s_add_u32 s14, s96, 0x1b720000
	s_addc_u32 s15, s97, 0
	s_add_u32 s14, s14, s6
	s_addc_u32 s15, s15, 0
	s_lshl_b32 s6, s18, 21
	s_add_u32 s16, s96, 0x1c800000
	s_addc_u32 s17, s97, 0
	s_add_u32 s16, s16, s6
	s_addc_u32 s17, s17, 0
	s_mov_b32 s12, s48
	s_nop 0
	s_nop 0
	s_nop 0
	s_nop 0
	s_nop 0
	s_nop 0
	s_nop 0
	s_nop 0

; template <int MB, bool PF2 = true>
; DI void gemm_main(const u16* __restrict__ A, int lda, const u16* __restrict__ B, int ldb, int K, f32x16 (&acc)[MB][2], GemmLds* s, int tid) {
;   const int lane = tid & 63, w = tid >> 6, r = lane & 31, h = lane >> 5, wm = w >> 1, wn = w & 1;
;   const int srow = tid >> 3, skc = (tid & 7) * 8;
;   const unsigned oa0 = (unsigned)(srow * lda + skc) * 2u, oa1 = oa0 + 64u * lda, oa2 = oa0 + 128u * lda, oa3 = oa0 + 192u * lda;
;   const unsigned ob0 = (unsigned)(srow * ldb + skc) * 2u, ob1 = ob0 + 64u * ldb, ob2 = ob0 + 128u * ldb, ob3 = ob0 + 192u * ldb;
; DI void phase_outproj(const Params& p, int l, char* smem, int tid) {
;   const int lane = tid & 63, w = tid >> 6, r = lane & 31, h = lane >> 5, wm = w >> 1, wn = w & 1;
;   GemmLds* s = (GemmLds*)smem;
;   const u16* ACC = p.Pk;
;   const bool dyn = (l == 0);
;   unsigned* qc = p.bar + 4096 + 384;
;   for (int it = (dyn ? fetch_item(qc, smem) : (int)blockIdx.x); it < 272 * 8; it = (dyn ? fetch_item(qc, smem) : it + (int)gridDim.x)) {
.LBB0_1221:
	s_or_b64 exec, exec, s[4:5]
	v_mov_b32_e32 v0, v206
	s_and_b64 vcc, exec, s[0:1]
	v_mov_b32_e32 v146, s48
	s_waitcnt lgkmcnt(0)
	s_barrier
	v_readlane_b32 s18, v254, 19
	v_and_b32_e32 v112, 63, v206
	v_lshrrev_b32_e32 v113, 6, v206
	v_lshrrev_b32_e32 v114, 3, v112
	v_lshl_add_u32 v114, v113, 5, v114
	v_lshlrev_b32_e32 v114, 11, v114
	v_and_b32_e32 v115, 7, v112
	v_lshrrev_b32_e32 v112, 4, v112
	v_xor_b32_e32 v115, v115, v112
	v_lshl_or_b32 v98, v115, 4, v114
	v_xor_b32_e32 v99, 64, v98
	v_add_u32_e32 v99, 16384, v99
	v_add_u32_e32 v100, 32768, v98
	v_add_u32_e32 v101, 32768, v99
	v_lshrrev_b32_e32 v156, 6, v206
	v_and_b32_e32 v112, 31, v206
	v_bfe_u32 v113, v206, 5, 1
	v_bfe_u32 v114, v112, 1, 3
	v_xor_b32_e32 v114, v114, v113
	v_lshlrev_b32_e32 v114, 4, v114
	v_lshl_or_b32 v114, v112, 7, v114
	v_lshrrev_b32_e32 v115, 7, v206
	v_lshl_add_u32 v102, v115, 13, v114
	v_bfe_u32 v115, v206, 6, 1
	v_lshl_add_u32 v106, v115, 13, v114
	v_add_u32_e32 v106, 0x4000, v106
	v_xor_b32_e32 v103, 32, v102
	v_xor_b32_e32 v107, 32, v106
	v_xor_b32_e32 v104, 64, v102
	v_xor_b32_e32 v108, 64, v106
	v_xor_b32_e32 v105, 96, v102
	v_xor_b32_e32 v109, 96, v106
	v_and_b32_e32 v112, 31, v206
	v_lshrrev_b32_e32 v113, 7, v206
	v_lshl_add_u32 v112, v113, 6, v112
	v_lshlrev_b32_e32 v112, 11, v112
	v_bfe_u32 v113, v206, 6, 1
	v_bfe_u32 v114, v206, 5, 1
	v_lshlrev_b32_e32 v115, 7, v113
	v_lshl_or_b32 v115, v114, 3, v115
	v_or_b32_e32 v110, v112, v115
	v_lshlrev_b32_e32 v111, 8, v113
	v_lshl_or_b32 v111, v114, 4, v111
	v_lshrrev_b32_e32 v112, 6, v206
	v_mul_u32_u24_e32 v112, 0x2400, v112
	v_and_b32_e32 v113, 31, v206
	v_mul_u32_u24_e32 v113, 0x90, v113
	v_bfe_u32 v114, v206, 5, 1
	v_lshl_add_u32 v113, v114, 3, v113
	v_add_u32_e32 v164, v112, v113
	v_bfe_u32 v113, v206, 3, 3
	v_mul_u32_u24_e32 v113, 0x90, v113
	v_and_b32_e32 v114, 7, v206
	v_lshl_add_u32 v113, v114, 4, v113
	v_add_u32_e32 v165, v112, v113
	v_bfe_u32 v112, v206, 3, 3
	v_lshrrev_b32_e32 v113, 7, v206
	v_lshl_add_u32 v112, v113, 6, v112
	v_mul_u32_u24_e32 v112, 0x800, v112
	v_bfe_u32 v113, v206, 6, 1
	v_lshlrev_b32_e32 v113, 7, v113
	v_and_b32_e32 v114, 7, v206
	v_lshl_or_b32 v113, v114, 4, v113
	v_add_u32_e32 v166, v112, v113
	v_readfirstlane_b32 s10, v156
	s_lshl_b32 s10, s10, 12
	s_lshl_b32 s6, s18, 21
	s_add_u32 s14, s96, 0x1cc00000
	s_addc_u32 s15, s97, 0
	s_add_u32 s14, s14, s6
	s_addc_u32 s15, s15, 0
	s_mov_b32 s12, s48
	s_nop 0
	s_nop 0
	s_nop 0
	s_nop 0
	s_nop 0
	s_nop 0
	s_nop 0
	s_nop 0
